# speedup vs baseline: 1.1261x; 1.0034x over previous
; DEV int tidx() { int t = threadIdx.x; asm volatile("" : "+v"(t)); return t; }
; DEV int bidx() { int b = __builtin_amdgcn_readfirstlane(blockIdx.x); asm volatile("" : "+s"(b)); return b; }
; DEV int gdim() { int g = __builtin_amdgcn_readfirstlane(gridDim.x); asm volatile("" : "+s"(g)); return g; }
; DEV float bf2f(u16 h) { return __uint_as_float(((unsigned)h) << 16); }
; #define ws (wsp(p))
; DEV void phase_gatenorm(const Params& p, int layer, char* smem) {
;   u16* sO = (u16*)smem;
;   char* ws = wsp(p);
;   const int tid = tidx();
;   const float* gn = p.in[10] + layer * 128;
;   u16* Z = (u16*)(ws + OFF_B);
;   for (int item = bidx(); item < 528 * 8; item += gdim()) {
;     const int ci = item >> 3, h = item & 7;
;     const bool smp = ci >= 512;
;     const int tok0 = smp ? T_P + (ci - 512) * 32 : ci * 64;
;     const ItemPtrs ip = item_ptrs(ws, ci, h);
; #pragma unroll
;     for (int i = 0; i < 4; i++) {
;       const int cc = tid + i * 256;
;       *(uint4*)(sO + cc * 8) = *(const uint4*)(ip.v + cc * 8);
;     }
;     __syncthreads();
;     const int j = tid >> 2, part = tid & 3;
;     float x[32], ss = 0.f;
; #pragma unroll
;     for (int i = 0; i < 32; i++) {
;       x[i] = bf2f(sO[((part * 2 + (i >> 4)) * 4 + (j >> 4)) * 256 + ((j >> 2) & 3) * 64 + (i & 15) * 4 + (j & 3)]);
;       ss += x[i] * x[i];
;     }
;     ss += __shfl_xor(ss, 1);
;     ss += __shfl_xor(ss, 2);
;     const float r = rsqrtf(ss * (1.f / 128.f) + EPS_);
;     if (!smp || j < 32) {
;       u16* zp = Z + (size_t)(tok0 + j) * 1024 + h * 128 + part * 32;
;       u32x4 zall[4];
; #pragma unroll
;       for (int g = 0; g < 4; g++) zall[g] = *(const u32x4*)(zp + g * 8);
.LBB0_1214:
	s_or_b64 exec, exec, s[0:1]
	s_mov_b64 s[4:5], s[62:63]
	v_mov_b32_e32 v0, v157
	s_mov_b32 s12, s52
	s_barrier
	s_cmpk_gt_i32 s12, 0x107f
	s_cbranch_scc1 .LBB0_1223
	v_and_b32_e32 v4, 64, v203
	v_xor_b32_e32 v2, 1, v203
	v_add_u32_e32 v4, 64, v4
	v_cmp_lt_i32_e32 vcc, v2, v4
	s_add_u32 s6, s4, 0xeb00000
	s_mov_b32 s9, s93
	v_readlane_b32 s16, v254, 0
	v_and_b32_e32 v3, 3, v0
	v_cndmask_b32_e32 v2, v203, v2, vcc
	s_addc_u32 s7, s5, 0
	s_lshl_b64 s[0:1], s[8:9], 2
	v_readlane_b32 s20, v254, 4
	v_lshlrev_b32_e32 v22, 3, v0
	v_ashrrev_i32_e32 v37, 2, v0
	v_lshlrev_b32_e32 v66, 2, v2
	v_xor_b32_e32 v2, 2, v203
	v_lshlrev_b32_e32 v68, 4, v0
	v_lshlrev_b32_e32 v0, 12, v3
	s_movk_i32 s8, 0x180
	v_readlane_b32 s21, v254, 5
	s_add_u32 s0, s20, s0
	v_cmp_lt_i32_e32 vcc, v2, v4
	v_and_b32_e32 v4, 0xfffffe00, v22
	v_and_or_b32 v0, v22, s8, v0
	s_addc_u32 s1, s21, s1
	v_cndmask_b32_e32 v2, v203, v2, vcc
	v_add_u32_e32 v0, v0, v4
	v_lshlrev_b32_e32 v4, 1, v37
	s_add_u32 s13, s4, 0x1de54400
	v_lshlrev_b32_e32 v67, 2, v2
	v_lshlrev_b32_e32 v2, 5, v3
	v_add_u32_e32 v24, 0x800, v22
	v_add_u32_e32 v26, 0x1000, v22
	v_add_u32_e32 v28, 0x1800, v22
	v_and_or_b32 v72, v4, 6, v0
	v_lshlrev_b32_e32 v0, 7, v3
	s_addc_u32 s14, s5, 0
	v_cmp_gt_i32_e64 s[2:3], 32, v37
	v_ashrrev_i32_e32 v23, 31, v22
	v_ashrrev_i32_e32 v25, 31, v24
	v_add_u32_e32 v69, 0x1000, v68
	v_ashrrev_i32_e32 v27, 31, v26
	v_add_u32_e32 v70, 0x2000, v68
	v_ashrrev_i32_e32 v29, 31, v28
	v_add_u32_e32 v71, 0x3000, v68
	v_lshl_add_u64 v[30:31], s[0:1], 0, v[0:1]
	v_lshlrev_b32_e32 v0, 1, v2
	v_readlane_b32 s17, v254, 1
	v_readlane_b32 s18, v254, 2
	v_readlane_b32 s19, v254, 3
	v_readlane_b32 s22, v254, 6
	v_readlane_b32 s23, v254, 7
	v_readlane_b32 s24, v254, 8
	v_readlane_b32 s25, v254, 9
	v_readlane_b32 s26, v254, 10
	v_readlane_b32 s27, v254, 11
	v_readlane_b32 s28, v254, 12
	v_readlane_b32 s29, v254, 13
	v_readlane_b32 s30, v254, 14
	v_readlane_b32 s31, v254, 15
	global_load_dwordx4 v[222:225], v[30:31], off
	global_load_dwordx4 v[226:229], v[30:31], off offset:16
	global_load_dwordx4 v[230:233], v[30:31], off offset:32
	global_load_dwordx4 v[234:237], v[30:31], off offset:48
	global_load_dwordx4 v[238:241], v[30:31], off offset:64
	global_load_dwordx4 v[242:245], v[30:31], off offset:80
	global_load_dwordx4 v[246:249], v[30:31], off offset:96
	global_load_dwordx4 v[250:253], v[30:31], off offset:112
	s_branch .LBB0_1217

; DEV float bf2f(u16 h) { return __uint_as_float(((unsigned)h) << 16); }
; #define ws (wsp(p))
; DEV void phase_gatenorm(const Params& p, int layer, char* smem) {
;     ...
;     const ItemPtrs ip = item_ptrs(ws, ci, h);
; #pragma unroll
;     for (int i = 0; i < 4; i++) {
;       const int cc = tid + i * 256;
;       *(uint4*)(sO + cc * 8) = *(const uint4*)(ip.v + cc * 8);
;     }
;     __syncthreads();
;     const int j = tid >> 2, part = tid & 3;
;     float x[32], ss = 0.f;
; #pragma unroll
;     for (int i = 0; i < 32; i++) {
;       x[i] = bf2f(sO[((part * 2 + (i >> 4)) * 4 + (j >> 4)) * 256 + ((j >> 2) & 3) * 64 + (i & 15) * 4 + (j & 3)]);
;       ss += x[i] * x[i];
;     }
;     ss += __shfl_xor(ss, 1);
;     ss += __shfl_xor(ss, 2);
.LBB0_1221:
	v_lshl_add_u64 v[2:3], v[22:23], 1, s[8:9]
	v_lshl_add_u64 v[6:7], v[24:25], 1, s[8:9]
	v_lshl_add_u64 v[10:11], v[26:27], 1, s[8:9]
	v_lshl_add_u64 v[14:15], v[28:29], 1, s[8:9]
	global_load_dwordx4 v[2:5], v[2:3], off
	s_nop 0
	global_load_dwordx4 v[6:9], v[6:7], off
	s_nop 0
	global_load_dwordx4 v[10:13], v[10:11], off
	s_nop 0
	global_load_dwordx4 v[14:17], v[14:15], off
	s_or_b64 s[10:11], s[2:3], s[0:1]
	s_waitcnt vmcnt(3)
	ds_write_b128 v68, v[2:5]
	s_waitcnt vmcnt(2)
	ds_write_b128 v69, v[6:9]
	s_waitcnt vmcnt(1)
	ds_write_b128 v70, v[10:13]
	s_waitcnt vmcnt(0)
	ds_write_b128 v71, v[14:17]
	s_waitcnt lgkmcnt(0)
	s_barrier
	ds_read_u16 v2, v72
	ds_read_u16 v3, v72 offset:8
	ds_read_u16 v4, v72 offset:16
	ds_read_u16 v5, v72 offset:24
	ds_read_u16 v6, v72 offset:32
	ds_read_u16 v7, v72 offset:40
	ds_read_u16 v8, v72 offset:48
	ds_read_u16 v9, v72 offset:56
	ds_read_u16 v10, v72 offset:64
	ds_read_u16 v11, v72 offset:72
	ds_read_u16 v12, v72 offset:80
	ds_read_u16 v13, v72 offset:88
	ds_read_u16 v14, v72 offset:96
	ds_read_u16 v15, v72 offset:104
	ds_read_u16 v16, v72 offset:112
	ds_read_u16 v17, v72 offset:120
	ds_read_u16 v20, v72 offset:2048
	ds_read_u16 v21, v72 offset:2056
	ds_read_u16 v32, v72 offset:2064
	ds_read_u16 v33, v72 offset:2072
	ds_read_u16 v34, v72 offset:2080
	ds_read_u16 v35, v72 offset:2088
	ds_read_u16 v36, v72 offset:2096
	ds_read_u16 v38, v72 offset:2104
	ds_read_u16 v39, v72 offset:2112
	ds_read_u16 v40, v72 offset:2120
	ds_read_u16 v73, v72 offset:2128
	ds_read_u16 v41, v72 offset:2136
	ds_read_u16 v82, v72 offset:2144
	ds_read_u16 v83, v72 offset:2152
	ds_read_u16 v84, v72 offset:2160
	ds_read_u16 v85, v72 offset:2168
	s_waitcnt lgkmcnt(14)
	v_lshlrev_b32_e32 v19, 16, v3
	v_lshlrev_b32_e32 v18, 16, v2
	v_lshlrev_b32_e32 v65, 16, v5
	v_lshlrev_b32_e32 v64, 16, v4
	v_pk_mul_f32 v[2:3], v[18:19], v[18:19]
	v_pk_mul_f32 v[4:5], v[64:65], v[64:65]
	v_add_f32_e32 v2, v2, v3
	v_lshlrev_b32_e32 v63, 16, v7
	v_lshlrev_b32_e32 v62, 16, v6
	v_add_f32_e32 v2, v2, v4
	v_pk_mul_f32 v[6:7], v[62:63], v[62:63]
	v_add_f32_e32 v2, v2, v5
	v_lshlrev_b32_e32 v61, 16, v9
	v_lshlrev_b32_e32 v60, 16, v8
	v_add_f32_e32 v2, v2, v6
	v_pk_mul_f32 v[8:9], v[60:61], v[60:61]
	v_add_f32_e32 v2, v2, v7
	v_lshlrev_b32_e32 v59, 16, v11
	v_lshlrev_b32_e32 v58, 16, v10
	v_add_f32_e32 v2, v2, v8
	v_pk_mul_f32 v[10:11], v[58:59], v[58:59]
	v_add_f32_e32 v2, v2, v9
	v_lshlrev_b32_e32 v57, 16, v13
	v_lshlrev_b32_e32 v56, 16, v12
	v_add_f32_e32 v2, v2, v10
	v_pk_mul_f32 v[12:13], v[56:57], v[56:57]
	v_add_f32_e32 v2, v2, v11
	v_lshlrev_b32_e32 v55, 16, v15
	v_lshlrev_b32_e32 v54, 16, v14
	v_add_f32_e32 v2, v2, v12
	v_pk_mul_f32 v[14:15], v[54:55], v[54:55]
	v_add_f32_e32 v2, v2, v13
	v_lshlrev_b32_e32 v53, 16, v17
	v_lshlrev_b32_e32 v52, 16, v16
	v_add_f32_e32 v2, v2, v14
	v_pk_mul_f32 v[16:17], v[52:53], v[52:53]
	v_add_f32_e32 v2, v2, v15
	v_lshlrev_b32_e32 v51, 16, v21
	v_lshlrev_b32_e32 v50, 16, v20
	v_add_f32_e32 v2, v2, v16
	v_pk_mul_f32 v[20:21], v[50:51], v[50:51]
	v_add_f32_e32 v2, v2, v17
	s_waitcnt lgkmcnt(12)
	v_lshlrev_b32_e32 v49, 16, v33
	v_lshlrev_b32_e32 v48, 16, v32
	v_add_f32_e32 v2, v2, v20
	v_pk_mul_f32 v[32:33], v[48:49], v[48:49]
	v_add_f32_e32 v2, v2, v21
	s_waitcnt lgkmcnt(10)
	v_lshlrev_b32_e32 v47, 16, v35
	v_lshlrev_b32_e32 v46, 16, v34
	v_add_f32_e32 v2, v2, v32
	v_pk_mul_f32 v[74:75], v[46:47], v[46:47]
	v_add_f32_e32 v2, v2, v33
	s_waitcnt lgkmcnt(8)
	v_lshlrev_b32_e32 v45, 16, v38
	v_lshlrev_b32_e32 v44, 16, v36
	v_add_f32_e32 v2, v2, v74
	v_pk_mul_f32 v[76:77], v[44:45], v[44:45]
	v_add_f32_e32 v2, v2, v75
	s_waitcnt lgkmcnt(6)
	v_lshlrev_b32_e32 v43, 16, v40
	v_lshlrev_b32_e32 v42, 16, v39
	v_add_f32_e32 v2, v2, v76
	v_pk_mul_f32 v[78:79], v[42:43], v[42:43]
	v_add_f32_e32 v2, v2, v77
	s_waitcnt lgkmcnt(4)
	v_lshlrev_b32_e32 v41, 16, v41
	v_lshlrev_b32_e32 v40, 16, v73
	v_add_f32_e32 v2, v2, v78
	v_pk_mul_f32 v[80:81], v[40:41], v[40:41]
	v_add_f32_e32 v2, v2, v79
	s_waitcnt lgkmcnt(2)
	v_lshlrev_b32_e32 v39, 16, v83
	v_lshlrev_b32_e32 v38, 16, v82
	v_add_f32_e32 v2, v2, v80
	v_pk_mul_f32 v[82:83], v[38:39], v[38:39]
	v_add_f32_e32 v2, v2, v81
	s_waitcnt lgkmcnt(0)
	v_lshlrev_b32_e32 v35, 16, v85
	v_lshlrev_b32_e32 v34, 16, v84
	v_add_f32_e32 v2, v2, v82
	v_pk_mul_f32 v[84:85], v[34:35], v[34:35]
	v_add_f32_e32 v2, v2, v83
	v_add_f32_e32 v2, v2, v84
	v_add_f32_e32 v2, v2, v85
	ds_bpermute_b32 v3, v66, v2
	s_waitcnt lgkmcnt(0)
	v_add_f32_e32 v2, v2, v3
	ds_bpermute_b32 v3, v67, v2
	s_and_saveexec_b64 s[8:9], s[10:11]
	s_cbranch_execz .LBB0_1216
; DEV float bf2f(u16 h) { return __uint_as_float(((unsigned)h) << 16); }
; DEV float siluf(float x) { return x * __builtin_amdgcn_rcpf(1.f + __expf(-x)); }
; DEV void phase_gatenorm(const Params& p, int layer, char* smem) {
;     ...
;     const float r = rsqrtf(ss * (1.f / 128.f) + EPS_);
;     if (!smp || j < 32) {
;       u16* zp = Z + (size_t)(tok0 + j) * 1024 + h * 128 + part * 32;
;       u32x4 zall[4];
; #pragma unroll
;       for (int g = 0; g < 4; g++) zall[g] = *(const u32x4*)(zp + g * 8);
;       __builtin_amdgcn_sched_barrier(0);
; #pragma unroll
;       for (int g = 0; g < 4; g++) {
;         const unsigned zz[4] = {zall[g][0], zall[g][1], zall[g][2], zall[g][3]};
;         unsigned o[4];
; #pragma unroll
;         for (int e = 0; e < 4; e++) {
;           const int i0 = g * 8 + e * 2;
;           const float z0 = bf2f((u16)(zz[e] & 0xffff)), z1 = bf2f((u16)(zz[e] >> 16));
;           o[e] = pack2(x[i0] * r * gn[part * 32 + i0] * siluf(z0), x[i0 + 1] * r * gn[part * 32 + i0 + 1] * siluf(z1));
;         }
;         *(uint4*)(zp + g * 8) = make_uint4(o[0], o[1], o[2], o[3]);
	s_waitcnt lgkmcnt(0)
	v_add_f32_e32 v2, v2, v3
	v_fmamk_f32 v2, v2, 0x3c000000, v156
	v_cmp_gt_f32_e32 vcc, s75, v2
	v_mul_f32_e32 v3, 0x4b800000, v2
	s_lshl_b32 s10, s16, 5
	v_cndmask_b32_e32 v2, v2, v3, vcc
	v_rsq_f32_e32 v2, v2
	s_addk_i32 s10, 0x4000
	s_lshl_b32 s11, s16, 6
	s_and_b64 s[0:1], s[0:1], exec
	s_cselect_b32 s0, s11, s10
	v_mul_f32_e32 v3, 0x45800000, v2
	v_cndmask_b32_e32 v36, v2, v3, vcc
	v_add_u32_e32 v2, s0, v37
	v_ashrrev_i32_e32 v3, 31, v2
	v_lshlrev_b64 v[2:3], 11, v[2:3]
	v_lshl_add_u64 v[2:3], s[6:7], 0, v[2:3]
	s_mov_b32 s1, s93
	s_lshl_b32 s0, s15, 8
	v_lshl_add_u64 v[2:3], v[2:3], 0, s[0:1]
	v_lshl_add_u64 v[32:33], v[2:3], 0, v[0:1]
	global_load_dwordx4 v[2:5], v[32:33], off offset:48
	global_load_dwordx4 v[6:9], v[32:33], off offset:32
	global_load_dwordx4 v[10:13], v[32:33], off offset:16
	global_load_dwordx4 v[14:17], v[32:33], off
	v_pk_mul_f32 v[82:83], v[36:37], v[18:19] op_sel_hi:[0,1]
	v_mov_b32_e32 v18, v226
	v_mov_b32_e32 v19, v227
	v_mov_b32_e32 v20, v228
	v_mov_b32_e32 v21, v229
	v_mov_b32_e32 v74, v222
	v_mov_b32_e32 v75, v223
	v_mov_b32_e32 v76, v224
	v_mov_b32_e32 v77, v225
	s_waitcnt vmcnt(0)
	v_lshlrev_b32_e32 v78, 16, v14
	v_and_b32_e32 v79, 0xffff0000, v14
	v_mul_f32_e32 v14, 0xbfb8aa3b, v78
	v_exp_f32_e32 v14, v14
	v_pk_mul_f32 v[64:65], v[36:37], v[64:65] op_sel_hi:[0,1]
	v_pk_mul_f32 v[62:63], v[36:37], v[62:63] op_sel_hi:[0,1]
	v_pk_mul_f32 v[60:61], v[36:37], v[60:61] op_sel_hi:[0,1]
	v_add_f32_e32 v14, 1.0, v14
	v_rcp_f32_e32 v80, v14
	v_mul_f32_e32 v14, 0xbfb8aa3b, v79
	v_exp_f32_e32 v14, v14
	v_pk_mul_f32 v[58:59], v[36:37], v[58:59] op_sel_hi:[0,1]
	v_pk_mul_f32 v[56:57], v[36:37], v[56:57] op_sel_hi:[0,1]
	v_pk_mul_f32 v[54:55], v[36:37], v[54:55] op_sel_hi:[0,1]
	v_add_f32_e32 v14, 1.0, v14
	v_rcp_f32_e32 v81, v14
	v_pk_mul_f32 v[50:51], v[36:37], v[50:51] op_sel_hi:[0,1]
	v_pk_mul_f32 v[78:79], v[80:81], v[78:79]
	v_pk_mul_f32 v[18:19], v[62:63], v[18:19]
	v_pk_mul_f32 v[74:75], v[82:83], v[74:75]
	v_pk_mul_f32 v[64:65], v[64:65], v[76:77]
	v_pk_mul_f32 v[74:75], v[74:75], v[78:79]
	v_pk_mul_f32 v[20:21], v[60:61], v[20:21]
	v_cvt_pk_bf16_f32 v14, v74, v75
	v_lshlrev_b32_e32 v74, 16, v15
	v_and_b32_e32 v75, 0xffff0000, v15
	v_mul_f32_e32 v15, 0xbfb8aa3b, v74
	v_exp_f32_e32 v15, v15
	v_lshlrev_b32_e32 v60, 16, v10
	v_and_b32_e32 v61, 0xffff0000, v10
	v_mul_f32_e32 v10, 0xbfb8aa3b, v60
	v_add_f32_e32 v15, 1.0, v15
	v_rcp_f32_e32 v78, v15
	v_mul_f32_e32 v15, 0xbfb8aa3b, v75
	v_exp_f32_e32 v15, v15
	v_exp_f32_e32 v10, v10
	v_add_f32_e32 v15, 1.0, v15
	v_rcp_f32_e32 v79, v15
	v_add_f32_e32 v10, 1.0, v10
	v_pk_mul_f32 v[74:75], v[78:79], v[74:75]
	s_nop 0
	v_pk_mul_f32 v[64:65], v[74:75], v[64:65]
	s_nop 0
	v_cvt_pk_bf16_f32 v15, v64, v65
	v_lshlrev_b32_e32 v64, 16, v16
	v_and_b32_e32 v65, 0xffff0000, v16
	v_mul_f32_e32 v16, 0xbfb8aa3b, v64
	v_exp_f32_e32 v16, v16
	s_nop 0
	v_add_f32_e32 v16, 1.0, v16
	v_rcp_f32_e32 v74, v16
	v_mul_f32_e32 v16, 0xbfb8aa3b, v65
	v_exp_f32_e32 v16, v16
	s_nop 0
	v_add_f32_e32 v16, 1.0, v16
	v_rcp_f32_e32 v75, v16
	s_nop 0
	v_pk_mul_f32 v[62:63], v[74:75], v[64:65]
	s_nop 0
	v_pk_mul_f32 v[18:19], v[62:63], v[18:19]
	s_nop 0
	v_cvt_pk_bf16_f32 v16, v18, v19
	v_lshlrev_b32_e32 v18, 16, v17
	v_and_b32_e32 v19, 0xffff0000, v17
	v_mul_f32_e32 v17, 0xbfb8aa3b, v18
	v_exp_f32_e32 v17, v17
	s_nop 0
	v_add_f32_e32 v17, 1.0, v17
	v_rcp_f32_e32 v62, v17
	v_mul_f32_e32 v17, 0xbfb8aa3b, v19
	v_exp_f32_e32 v17, v17
	s_nop 0
	v_add_f32_e32 v17, 1.0, v17
	v_rcp_f32_e32 v63, v17
	s_nop 0
	v_pk_mul_f32 v[18:19], v[62:63], v[18:19]
	s_nop 0
	v_pk_mul_f32 v[18:19], v[18:19], v[20:21]
	v_rcp_f32_e32 v62, v10
	v_cvt_pk_bf16_f32 v17, v18, v19
	global_store_dwordx4 v[32:33], v[14:17], off
	s_nop 1
	v_mov_b32_e32 v14, v234
	v_mov_b32_e32 v15, v235
	v_mov_b32_e32 v16, v236
	v_mov_b32_e32 v17, v237
	v_mov_b32_e32 v18, v230
	v_mov_b32_e32 v19, v231
	v_mov_b32_e32 v20, v232
	v_mov_b32_e32 v21, v233
	v_mul_f32_e32 v10, 0xbfb8aa3b, v61
	v_exp_f32_e32 v10, v10
	v_pk_mul_f32 v[14:15], v[54:55], v[14:15]
	v_add_f32_e32 v10, 1.0, v10
	v_rcp_f32_e32 v63, v10
	v_pk_mul_f32 v[18:19], v[58:59], v[18:19]
	v_pk_mul_f32 v[20:21], v[56:57], v[20:21]
	v_pk_mul_f32 v[58:59], v[62:63], v[60:61]
	s_nop 0
	v_pk_mul_f32 v[18:19], v[58:59], v[18:19]
	s_nop 0
	v_cvt_pk_bf16_f32 v10, v18, v19
	v_lshlrev_b32_e32 v18, 16, v11
	v_and_b32_e32 v19, 0xffff0000, v11
	v_mul_f32_e32 v11, 0xbfb8aa3b, v18
	v_exp_f32_e32 v11, v11
	s_nop 0
	v_add_f32_e32 v11, 1.0, v11
	v_rcp_f32_e32 v58, v11
	v_mul_f32_e32 v11, 0xbfb8aa3b, v19
	v_exp_f32_e32 v11, v11
	s_nop 0
	v_add_f32_e32 v11, 1.0, v11
	v_rcp_f32_e32 v59, v11
	s_nop 0
	v_pk_mul_f32 v[18:19], v[58:59], v[18:19]
	s_nop 0
	v_pk_mul_f32 v[18:19], v[18:19], v[20:21]
	s_nop 0
	v_cvt_pk_bf16_f32 v11, v18, v19
	v_lshlrev_b32_e32 v18, 16, v12
	v_and_b32_e32 v19, 0xffff0000, v12
	v_mul_f32_e32 v12, 0xbfb8aa3b, v18
	v_exp_f32_e32 v12, v12
	s_nop 0
	v_add_f32_e32 v12, 1.0, v12
	v_rcp_f32_e32 v20, v12
	v_mul_f32_e32 v12, 0xbfb8aa3b, v19
	v_exp_f32_e32 v12, v12
	s_nop 0
	v_add_f32_e32 v12, 1.0, v12
	v_rcp_f32_e32 v21, v12
	s_nop 0
	v_pk_mul_f32 v[18:19], v[20:21], v[18:19]
	s_nop 0
	v_pk_mul_f32 v[14:15], v[18:19], v[14:15]
	v_pk_mul_f32 v[20:21], v[36:37], v[52:53] op_sel_hi:[0,1]
; DEV float bf2f(u16 h) { return __uint_as_float(((unsigned)h) << 16); }
; DEV float siluf(float x) { return x * __builtin_amdgcn_rcpf(1.f + __expf(-x)); }
; DEV void phase_gatenorm(const Params& p, int layer, char* smem) {
;     ...
;       for (int g = 0; g < 4; g++) {
;         const unsigned zz[4] = {zall[g][0], zall[g][1], zall[g][2], zall[g][3]};
;         unsigned o[4];
; #pragma unroll
;         for (int e = 0; e < 4; e++) {
;           const int i0 = g * 8 + e * 2;
;           const float z0 = bf2f((u16)(zz[e] & 0xffff)), z1 = bf2f((u16)(zz[e] >> 16));
;           o[e] = pack2(x[i0] * r * gn[part * 32 + i0] * siluf(z0), x[i0 + 1] * r * gn[part * 32 + i0 + 1] * siluf(z1));
;         }
;         *(uint4*)(zp + g * 8) = make_uint4(o[0], o[1], o[2], o[3]);
;       }
	v_cvt_pk_bf16_f32 v12, v14, v15
	v_lshlrev_b32_e32 v14, 16, v13
	v_and_b32_e32 v15, 0xffff0000, v13
	v_mul_f32_e32 v13, 0xbfb8aa3b, v14
	v_exp_f32_e32 v13, v13
	v_pk_mul_f32 v[16:17], v[20:21], v[16:17]
	v_add_f32_e32 v13, 1.0, v13
	v_rcp_f32_e32 v18, v13
	v_mul_f32_e32 v13, 0xbfb8aa3b, v15
	v_exp_f32_e32 v13, v13
	s_nop 0
	v_add_f32_e32 v13, 1.0, v13
	v_rcp_f32_e32 v19, v13
	s_nop 0
	v_pk_mul_f32 v[14:15], v[18:19], v[14:15]
	s_nop 0
	v_pk_mul_f32 v[14:15], v[14:15], v[16:17]
	v_lshlrev_b32_e32 v18, 16, v6
	v_cvt_pk_bf16_f32 v13, v14, v15
	global_store_dwordx4 v[32:33], v[10:13], off offset:16
	s_nop 1
	v_mov_b32_e32 v10, v242
	v_mov_b32_e32 v11, v243
	v_mov_b32_e32 v12, v244
	v_mov_b32_e32 v13, v245
	v_mov_b32_e32 v14, v238
	v_mov_b32_e32 v15, v239
	v_mov_b32_e32 v16, v240
	v_mov_b32_e32 v17, v241
	v_and_b32_e32 v19, 0xffff0000, v6
	v_mul_f32_e32 v6, 0xbfb8aa3b, v18
	v_exp_f32_e32 v6, v6
	v_pk_mul_f32 v[14:15], v[50:51], v[14:15]
	v_add_f32_e32 v6, 1.0, v6
	v_rcp_f32_e32 v20, v6
	v_mul_f32_e32 v6, 0xbfb8aa3b, v19
	v_exp_f32_e32 v6, v6
	s_nop 0
	v_add_f32_e32 v6, 1.0, v6
	v_rcp_f32_e32 v21, v6
	s_nop 0
	v_pk_mul_f32 v[18:19], v[20:21], v[18:19]
	s_nop 0
	v_pk_mul_f32 v[14:15], v[18:19], v[14:15]
	v_pk_mul_f32 v[20:21], v[36:37], v[48:49] op_sel_hi:[0,1]
	v_cvt_pk_bf16_f32 v6, v14, v15
	v_lshlrev_b32_e32 v14, 16, v7
	v_and_b32_e32 v15, 0xffff0000, v7
	v_mul_f32_e32 v7, 0xbfb8aa3b, v14
	v_exp_f32_e32 v7, v7
	v_pk_mul_f32 v[16:17], v[20:21], v[16:17]
	v_add_f32_e32 v7, 1.0, v7
	v_rcp_f32_e32 v18, v7
	v_mul_f32_e32 v7, 0xbfb8aa3b, v15
	v_exp_f32_e32 v7, v7
	s_nop 0
	v_add_f32_e32 v7, 1.0, v7
	v_rcp_f32_e32 v19, v7
	s_nop 0
	v_pk_mul_f32 v[14:15], v[18:19], v[14:15]
	s_nop 0
	v_pk_mul_f32 v[14:15], v[14:15], v[16:17]
	v_pk_mul_f32 v[18:19], v[36:37], v[46:47] op_sel_hi:[0,1]
	v_cvt_pk_bf16_f32 v7, v14, v15
	v_lshlrev_b32_e32 v14, 16, v8
	v_and_b32_e32 v15, 0xffff0000, v8
	v_mul_f32_e32 v8, 0xbfb8aa3b, v14
	v_exp_f32_e32 v8, v8
	v_pk_mul_f32 v[10:11], v[18:19], v[10:11]
	v_pk_mul_f32 v[18:19], v[36:37], v[42:43] op_sel_hi:[0,1]
	v_add_f32_e32 v8, 1.0, v8
	v_rcp_f32_e32 v16, v8
	v_mul_f32_e32 v8, 0xbfb8aa3b, v15
	v_exp_f32_e32 v8, v8
	s_nop 0
	v_add_f32_e32 v8, 1.0, v8
	v_rcp_f32_e32 v17, v8
	s_nop 0
	v_pk_mul_f32 v[14:15], v[16:17], v[14:15]
	s_nop 0
	v_pk_mul_f32 v[10:11], v[14:15], v[10:11]
	v_pk_mul_f32 v[16:17], v[36:37], v[44:45] op_sel_hi:[0,1]
	v_cvt_pk_bf16_f32 v8, v10, v11
	v_lshlrev_b32_e32 v10, 16, v9
	v_and_b32_e32 v11, 0xffff0000, v9
	v_mul_f32_e32 v9, 0xbfb8aa3b, v10
	v_exp_f32_e32 v9, v9
	v_pk_mul_f32 v[12:13], v[16:17], v[12:13]
	v_add_f32_e32 v9, 1.0, v9
	v_rcp_f32_e32 v14, v9
	v_mul_f32_e32 v9, 0xbfb8aa3b, v11
	v_exp_f32_e32 v9, v9
	s_nop 0
	v_add_f32_e32 v9, 1.0, v9
	v_rcp_f32_e32 v15, v9
	s_nop 0
	v_pk_mul_f32 v[10:11], v[14:15], v[10:11]
	s_nop 0
	v_pk_mul_f32 v[10:11], v[10:11], v[12:13]
	v_lshlrev_b32_e32 v14, 16, v2
	v_cvt_pk_bf16_f32 v9, v10, v11
	global_store_dwordx4 v[32:33], v[6:9], off offset:32
	s_nop 1
	v_mov_b32_e32 v6, v250
	v_mov_b32_e32 v7, v251
	v_mov_b32_e32 v8, v252
	v_mov_b32_e32 v9, v253
	v_mov_b32_e32 v10, v246
	v_mov_b32_e32 v11, v247
	v_mov_b32_e32 v12, v248
	v_mov_b32_e32 v13, v249
	v_and_b32_e32 v15, 0xffff0000, v2
	v_mul_f32_e32 v2, 0xbfb8aa3b, v14
	v_exp_f32_e32 v2, v2
	v_pk_mul_f32 v[10:11], v[18:19], v[10:11]
	v_add_f32_e32 v2, 1.0, v2
	v_rcp_f32_e32 v16, v2
	v_mul_f32_e32 v2, 0xbfb8aa3b, v15
	v_exp_f32_e32 v2, v2
	s_nop 0
	v_add_f32_e32 v2, 1.0, v2
	v_rcp_f32_e32 v17, v2
	s_nop 0
	v_pk_mul_f32 v[14:15], v[16:17], v[14:15]
	s_nop 0
	v_pk_mul_f32 v[10:11], v[14:15], v[10:11]
	v_pk_mul_f32 v[16:17], v[36:37], v[40:41] op_sel_hi:[0,1]
	v_cvt_pk_bf16_f32 v2, v10, v11
	v_lshlrev_b32_e32 v10, 16, v3
	v_and_b32_e32 v11, 0xffff0000, v3
	v_mul_f32_e32 v3, 0xbfb8aa3b, v10
	v_exp_f32_e32 v3, v3
	v_pk_mul_f32 v[12:13], v[16:17], v[12:13]
	v_add_f32_e32 v3, 1.0, v3
	v_rcp_f32_e32 v14, v3
	v_mul_f32_e32 v3, 0xbfb8aa3b, v11
	v_exp_f32_e32 v3, v3
	s_nop 0
	v_add_f32_e32 v3, 1.0, v3
	v_rcp_f32_e32 v15, v3
	s_nop 0
	v_pk_mul_f32 v[10:11], v[14:15], v[10:11]
	s_nop 0
	v_pk_mul_f32 v[10:11], v[10:11], v[12:13]
	v_pk_mul_f32 v[14:15], v[36:37], v[38:39] op_sel_hi:[0,1]
	v_cvt_pk_bf16_f32 v3, v10, v11
	v_lshlrev_b32_e32 v10, 16, v4
	v_and_b32_e32 v11, 0xffff0000, v4
	v_mul_f32_e32 v4, 0xbfb8aa3b, v10
	v_exp_f32_e32 v4, v4
	v_pk_mul_f32 v[6:7], v[14:15], v[6:7]
	v_add_f32_e32 v4, 1.0, v4
	v_rcp_f32_e32 v12, v4
	v_mul_f32_e32 v4, 0xbfb8aa3b, v11
	v_exp_f32_e32 v4, v4
	s_nop 0
	v_add_f32_e32 v4, 1.0, v4
	v_rcp_f32_e32 v13, v4
	s_nop 0
	v_pk_mul_f32 v[10:11], v[12:13], v[10:11]
	s_nop 0
	v_pk_mul_f32 v[6:7], v[10:11], v[6:7]
	v_pk_mul_f32 v[12:13], v[36:37], v[34:35] op_sel_hi:[0,1]
	v_cvt_pk_bf16_f32 v4, v6, v7
	v_lshlrev_b32_e32 v6, 16, v5
	v_and_b32_e32 v7, 0xffff0000, v5
	v_mul_f32_e32 v5, 0xbfb8aa3b, v6
	v_exp_f32_e32 v5, v5
	v_pk_mul_f32 v[8:9], v[12:13], v[8:9]
	v_add_f32_e32 v5, 1.0, v5
	v_rcp_f32_e32 v10, v5
	v_mul_f32_e32 v5, 0xbfb8aa3b, v7
	v_exp_f32_e32 v5, v5
	s_nop 0
	v_add_f32_e32 v5, 1.0, v5
	v_rcp_f32_e32 v11, v5
	s_nop 0
	v_pk_mul_f32 v[6:7], v[10:11], v[6:7]
	s_nop 0
	v_pk_mul_f32 v[6:7], v[6:7], v[8:9]
	s_nop 0
	v_cvt_pk_bf16_f32 v5, v6, v7
	global_store_dwordx4 v[32:33], v[2:5], off offset:48
	s_nop 1
	s_branch .LBB0_1216
